# S7: S4 + wr0 (leading half) at s_setprio 1 during the gate/up SwiGLU epilogues, reset to 0 at epilogue end
# speedup vs baseline: 1.0078x; 1.0078x over previous
.Lkmid_0:
	s_add_i32 s0, 0, 0x18000
	s_add_i32 s1, 0, 0x1c000
	ds_read_b128 v[144:147], v250 offset:32768
	ds_read_b128 v[148:151], v250 offset:33792
	ds_read_b128 v[152:155], v250 offset:34816
	ds_read_b128 v[156:159], v250 offset:35840
	ds_read_b128 v[160:163], v250 offset:49152
	ds_read_b128 v[164:167], v250 offset:50176
	ds_read_b128 v[168:171], v250 offset:51200
	ds_read_b128 v[172:175], v250 offset:52224
	s_add_u32 s58, s58, 0x80000
	s_addc_u32 s59, s59, 0
	s_mov_b32 m0, s29
	ds_read_b128 v[176:179], v143 offset:32768
	ds_read_b128 v[180:183], v143 offset:33792
	ds_read_b128 v[184:187], v143 offset:34816
	ds_read_b128 v[188:191], v143 offset:35840
	ds_read_b128 v[192:195], v143 offset:36864
	ds_read_b128 v[202:205], v143 offset:37888
	ds_read_b128 v[206:209], v143 offset:38912
	ds_read_b128 v[210:213], v143 offset:39936
	global_load_lds_dwordx4 v134, s[58:59]
	s_mov_b32 m0, s30
	s_nop 0
	global_load_lds_dwordx4 v132, s[58:59]
	s_waitcnt vmcnt(8)
	s_waitcnt lgkmcnt(0)
	s_setprio 1
	s_barrier
	v_mfma_f32_16x16x32_bf16 v[126:129], v[144:147], v[176:179], v[126:129]
	v_mfma_f32_16x16x32_bf16 v[118:121], v[152:155], v[176:179], v[118:121]
	v_mfma_f32_16x16x32_bf16 v[110:113], v[144:147], v[184:187], v[110:113]
	v_mfma_f32_16x16x32_bf16 v[102:105], v[152:155], v[184:187], v[102:105]
	v_mfma_f32_16x16x32_bf16 v[94:97], v[144:147], v[192:195], v[94:97]
	v_mfma_f32_16x16x32_bf16 v[86:89], v[152:155], v[192:195], v[86:89]
	v_mfma_f32_16x16x32_bf16 v[78:81], v[144:147], v[206:209], v[78:81]
	v_mfma_f32_16x16x32_bf16 v[70:73], v[152:155], v[206:209], v[70:73]
	v_mfma_f32_16x16x32_bf16 v[126:129], v[148:151], v[180:183], v[126:129]
	v_mfma_f32_16x16x32_bf16 v[118:121], v[156:159], v[180:183], v[118:121]
	v_mfma_f32_16x16x32_bf16 v[110:113], v[148:151], v[188:191], v[110:113]
	v_mfma_f32_16x16x32_bf16 v[102:105], v[156:159], v[188:191], v[102:105]
	v_mfma_f32_16x16x32_bf16 v[94:97], v[148:151], v[202:205], v[94:97]
	v_mfma_f32_16x16x32_bf16 v[86:89], v[156:159], v[202:205], v[86:89]
	v_mfma_f32_16x16x32_bf16 v[78:81], v[148:151], v[210:213], v[78:81]
	v_mfma_f32_16x16x32_bf16 v[70:73], v[156:159], v[210:213], v[70:73]
	v_mfma_f32_16x16x32_bf16 v[122:125], v[160:163], v[176:179], v[122:125]
	v_mfma_f32_16x16x32_bf16 v[114:117], v[168:171], v[176:179], v[114:117]
	v_mfma_f32_16x16x32_bf16 v[106:109], v[160:163], v[184:187], v[106:109]
	v_mfma_f32_16x16x32_bf16 v[98:101], v[168:171], v[184:187], v[98:101]
	v_mfma_f32_16x16x32_bf16 v[90:93], v[160:163], v[192:195], v[90:93]
	v_mfma_f32_16x16x32_bf16 v[82:85], v[168:171], v[192:195], v[82:85]
	v_mfma_f32_16x16x32_bf16 v[74:77], v[160:163], v[206:209], v[74:77]
	v_mfma_f32_16x16x32_bf16 v[66:69], v[168:171], v[206:209], v[66:69]
	v_mfma_f32_16x16x32_bf16 v[122:125], v[164:167], v[180:183], v[122:125]
	v_mfma_f32_16x16x32_bf16 v[114:117], v[172:175], v[180:183], v[114:117]
	v_mfma_f32_16x16x32_bf16 v[106:109], v[164:167], v[188:191], v[106:109]
	v_mfma_f32_16x16x32_bf16 v[98:101], v[172:175], v[188:191], v[98:101]
	v_mfma_f32_16x16x32_bf16 v[90:93], v[164:167], v[202:205], v[90:93]
	v_mfma_f32_16x16x32_bf16 v[82:85], v[172:175], v[202:205], v[82:85]
	v_mfma_f32_16x16x32_bf16 v[74:77], v[164:167], v[210:213], v[74:77]
	v_mfma_f32_16x16x32_bf16 v[66:69], v[172:175], v[210:213], v[66:69]
	s_barrier
	s_setprio 0
	s_add_i32 s0, s0, s26
	s_mov_b32 m0, s0
	ds_read_b128 v[176:179], v143 offset:49152
	ds_read_b128 v[180:183], v143 offset:50176
	ds_read_b128 v[184:187], v143 offset:51200
	ds_read_b128 v[188:191], v143 offset:52224
	ds_read_b128 v[192:195], v143 offset:53248
	ds_read_b128 v[202:205], v143 offset:54272
	ds_read_b128 v[206:209], v143 offset:55296
	ds_read_b128 v[210:213], v143 offset:56320
	global_load_lds_dwordx4 v196, s[98:99]
	s_add_i32 m0, s0, 0x2000
	s_add_u32 s8, s8, 0x80080
	s_addc_u32 s9, s9, 0
	s_add_i32 s0, s1, s26
	global_load_lds_dwordx4 v130, s[98:99]
	s_mov_b32 m0, s0
	s_nop 0
	global_load_lds_dwordx4 v196, s[8:9]
	s_add_i32 m0, s0, 0x2000
	s_nop 0
	global_load_lds_dwordx4 v130, s[8:9]
	s_mov_b32 m0, s31
	s_nop 0
	global_load_lds_dwordx4 v134, s[78:79]
	s_mov_b32 m0, s34
	s_nop 0
	global_load_lds_dwordx4 v132, s[78:79]
	s_waitcnt vmcnt(8)
	s_waitcnt lgkmcnt(0)
	s_setprio 1
	s_barrier
	v_mfma_f32_16x16x32_bf16 v[62:65], v[144:147], v[176:179], v[62:65]
	v_mfma_f32_16x16x32_bf16 v[54:57], v[152:155], v[176:179], v[54:57]
	v_mfma_f32_16x16x32_bf16 v[46:49], v[144:147], v[184:187], v[46:49]
	v_mfma_f32_16x16x32_bf16 v[38:41], v[152:155], v[184:187], v[38:41]
	v_mfma_f32_16x16x32_bf16 v[30:33], v[144:147], v[192:195], v[30:33]
	v_mfma_f32_16x16x32_bf16 v[22:25], v[152:155], v[192:195], v[22:25]
	v_mfma_f32_16x16x32_bf16 v[14:17], v[144:147], v[206:209], v[14:17]
	v_mfma_f32_16x16x32_bf16 v[6:9], v[152:155], v[206:209], v[6:9]
	v_mfma_f32_16x16x32_bf16 v[62:65], v[148:151], v[180:183], v[62:65]
	v_mfma_f32_16x16x32_bf16 v[54:57], v[156:159], v[180:183], v[54:57]
	v_mfma_f32_16x16x32_bf16 v[46:49], v[148:151], v[188:191], v[46:49]
	v_mfma_f32_16x16x32_bf16 v[38:41], v[156:159], v[188:191], v[38:41]
	v_mfma_f32_16x16x32_bf16 v[30:33], v[148:151], v[202:205], v[30:33]
	v_mfma_f32_16x16x32_bf16 v[22:25], v[156:159], v[202:205], v[22:25]
	v_mfma_f32_16x16x32_bf16 v[14:17], v[148:151], v[210:213], v[14:17]
	v_mfma_f32_16x16x32_bf16 v[6:9], v[156:159], v[210:213], v[6:9]
	v_mfma_f32_16x16x32_bf16 v[58:61], v[160:163], v[176:179], v[58:61]
	v_mfma_f32_16x16x32_bf16 v[50:53], v[168:171], v[176:179], v[50:53]
	v_mfma_f32_16x16x32_bf16 v[42:45], v[160:163], v[184:187], v[42:45]
	v_mfma_f32_16x16x32_bf16 v[34:37], v[168:171], v[184:187], v[34:37]
	v_mfma_f32_16x16x32_bf16 v[26:29], v[160:163], v[192:195], v[26:29]
	v_mfma_f32_16x16x32_bf16 v[18:21], v[168:171], v[192:195], v[18:21]
	v_mfma_f32_16x16x32_bf16 v[10:13], v[160:163], v[206:209], v[10:13]
	v_mfma_f32_16x16x32_bf16 v[2:5], v[168:171], v[206:209], v[2:5]
	v_mfma_f32_16x16x32_bf16 v[58:61], v[164:167], v[180:183], v[58:61]
	v_mfma_f32_16x16x32_bf16 v[50:53], v[172:175], v[180:183], v[50:53]
	v_mfma_f32_16x16x32_bf16 v[42:45], v[164:167], v[188:191], v[42:45]
	v_mfma_f32_16x16x32_bf16 v[34:37], v[172:175], v[188:191], v[34:37]
	v_mfma_f32_16x16x32_bf16 v[26:29], v[164:167], v[202:205], v[26:29]
	v_mfma_f32_16x16x32_bf16 v[18:21], v[172:175], v[202:205], v[18:21]
	v_mfma_f32_16x16x32_bf16 v[10:13], v[164:167], v[210:213], v[10:13]
	v_mfma_f32_16x16x32_bf16 v[2:5], v[172:175], v[210:213], v[2:5]
	s_barrier
	s_setprio 0
	s_add_u32 s67, s67, 0x100
	s_addc_u32 s68, s68, 0
	s_add_u32 s52, s52, 0x100
	s_addc_u32 s53, s53, 0
	s_cmp_ge_i32 s69, s62
	s_mov_b32 s8, s69
	s_cbranch_scc0 .LBB0_904
	s_and_b64 vcc, exec, s[38:39]
	s_cbranch_vccz .LBB0_907
	s_barrier
	s_setprio 1
.LBB0_907:
	v_mul_f32_e32 v145, 0xbfb8aa3b, v126
	v_exp_f32_e32 v145, v145
	v_lshl_or_b32 v146, s63, 7, v142
	v_lshl_add_u32 v144, s64, 8, v140
	v_ashrrev_i32_e32 v147, 31, v146
	v_add_f32_e32 v145, 1.0, v145
	v_rcp_f32_e32 v145, v145
	s_movk_i32 s0, 0x2b00
	s_andn2_b64 vcc, exec, s[46:47]
	s_mov_b64 s[66:67], 0x3000
	v_mul_f32_e32 v126, v126, v145
	v_mul_f32_e32 v122, v126, v122
	v_mul_f32_e32 v126, 0xbfb8aa3b, v118
	v_exp_f32_e32 v126, v126
	s_nop 0
	v_add_f32_e32 v126, 1.0, v126
	v_rcp_f32_e32 v126, v126
	s_nop 0
	v_mul_f32_e32 v118, v118, v126
	v_mul_f32_e32 v114, v118, v114
	v_mul_f32_e32 v118, 0xbfb8aa3b, v127
	v_exp_f32_e32 v118, v118
	s_nop 0
	v_add_f32_e32 v118, 1.0, v118
	v_rcp_f32_e32 v118, v118
	s_nop 0
	v_mul_f32_e32 v118, v127, v118
	v_mul_f32_e32 v118, v118, v123
	v_mul_f32_e32 v123, 0xbfb8aa3b, v119
	v_exp_f32_e32 v123, v123
	v_cvt_pk_bf16_f32 v118, v122, v118
	s_nop 0
	v_add_f32_e32 v123, 1.0, v123
	v_rcp_f32_e32 v123, v123
	s_nop 0
	v_mul_f32_e32 v119, v119, v123
	v_mul_f32_e32 v123, 0xbfb8aa3b, v120
	v_exp_f32_e32 v123, v123
	v_mul_f32_e32 v115, v119, v115
	v_mul_f32_e32 v119, 0xbfb8aa3b, v128
	v_exp_f32_e32 v119, v119
	v_add_f32_e32 v123, 1.0, v123
	v_rcp_f32_e32 v123, v123
	v_add_f32_e32 v119, 1.0, v119
	v_rcp_f32_e32 v119, v119
	v_mul_f32_e32 v120, v120, v123
	v_mul_f32_e32 v116, v120, v116
	v_mul_f32_e32 v120, 0xbfb8aa3b, v129
	v_exp_f32_e32 v120, v120
	v_mul_f32_e32 v123, 0xbfb8aa3b, v121
	v_exp_f32_e32 v123, v123
	v_mul_f32_e32 v119, v128, v119
	v_add_f32_e32 v120, 1.0, v120
	v_rcp_f32_e32 v120, v120
	v_add_f32_e32 v123, 1.0, v123
	v_rcp_f32_e32 v123, v123
	v_mul_f32_e32 v119, v119, v124
	v_mul_f32_e32 v120, v129, v120
	v_mul_f32_e32 v120, v120, v125
	v_mul_f32_e32 v121, v121, v123
	v_mul_f32_e32 v117, v121, v117
	v_cvt_pk_bf16_f32 v119, v119, v120
	v_cvt_pk_bf16_f32 v120, v114, v115
	v_mov_b64_e32 v[114:115], s[6:7]
	v_cvt_pk_bf16_f32 v121, v116, v117
	v_mad_i64_i32 v[122:123], s[8:9], v144, s0, v[114:115]
	v_lshlrev_b64 v[116:117], 1, v[146:147]
	v_lshl_add_u64 v[122:123], v[122:123], 0, v[116:117]
	global_store_dwordx4 v[122:123], v[118:121], off
	s_nop 1
	v_mul_f32_e32 v118, 0xbfb8aa3b, v110
	v_exp_f32_e32 v118, v118
	s_nop 0
	v_add_f32_e32 v118, 1.0, v118
	v_rcp_f32_e32 v118, v118
	s_nop 0
	v_mul_f32_e32 v110, v110, v118
	v_mul_f32_e32 v106, v110, v106
	v_mul_f32_e32 v110, 0xbfb8aa3b, v102
	v_exp_f32_e32 v110, v110
	s_nop 0
	v_add_f32_e32 v110, 1.0, v110
	v_rcp_f32_e32 v110, v110
	s_nop 0
	v_mul_f32_e32 v102, v102, v110
	v_mul_f32_e32 v102, v102, v98
	v_mul_f32_e32 v98, 0xbfb8aa3b, v111
	v_exp_f32_e32 v98, v98
	s_nop 0
	v_add_f32_e32 v98, 1.0, v98
	v_rcp_f32_e32 v98, v98
	s_nop 0
	v_mul_f32_e32 v98, v111, v98
	v_mul_f32_e32 v98, v98, v107
	v_mul_f32_e32 v107, 0xbfb8aa3b, v103
	v_exp_f32_e32 v107, v107
	v_cvt_pk_bf16_f32 v98, v106, v98
	s_nop 0
	v_add_f32_e32 v107, 1.0, v107
	v_rcp_f32_e32 v107, v107
	s_nop 0
	v_mul_f32_e32 v103, v103, v107
	v_mul_f32_e32 v107, 0xbfb8aa3b, v104
	v_exp_f32_e32 v107, v107
	v_mul_f32_e32 v103, v103, v99
	v_mul_f32_e32 v99, 0xbfb8aa3b, v112
	v_exp_f32_e32 v99, v99
	v_add_f32_e32 v107, 1.0, v107
	v_rcp_f32_e32 v107, v107
	v_add_f32_e32 v99, 1.0, v99
	v_rcp_f32_e32 v99, v99
	v_mul_f32_e32 v104, v104, v107
	v_mul_f32_e32 v104, v104, v100
	v_mul_f32_e32 v100, 0xbfb8aa3b, v113
	v_exp_f32_e32 v100, v100
	v_mul_f32_e32 v107, 0xbfb8aa3b, v105
	v_exp_f32_e32 v107, v107
	v_mul_f32_e32 v99, v112, v99
	v_add_f32_e32 v100, 1.0, v100
	v_rcp_f32_e32 v100, v100
	v_add_f32_e32 v107, 1.0, v107
	v_rcp_f32_e32 v107, v107
	v_mul_f32_e32 v99, v99, v108
	v_mul_f32_e32 v100, v113, v100
	v_mul_f32_e32 v100, v100, v109
	v_cvt_pk_bf16_f32 v99, v99, v100
	v_cvt_pk_bf16_f32 v100, v102, v103
	v_or_b32_e32 v102, 16, v144
	v_mul_f32_e32 v105, v105, v107
	v_mad_i64_i32 v[102:103], s[8:9], v102, s0, v[114:115]
	v_mul_f32_e32 v101, v105, v101
	v_lshl_add_u64 v[102:103], v[102:103], 0, v[116:117]
	v_cvt_pk_bf16_f32 v101, v104, v101
	global_store_dwordx4 v[102:103], v[98:101], off
	s_nop 1
	v_mul_f32_e32 v98, 0xbfb8aa3b, v94
	v_exp_f32_e32 v98, v98
	s_nop 0
	v_add_f32_e32 v98, 1.0, v98
	v_rcp_f32_e32 v98, v98
	s_nop 0
	v_mul_f32_e32 v94, v94, v98
	v_mul_f32_e32 v90, v94, v90
	v_mul_f32_e32 v94, 0xbfb8aa3b, v86
	v_exp_f32_e32 v94, v94
	s_nop 0
	v_add_f32_e32 v94, 1.0, v94
	v_rcp_f32_e32 v94, v94
	s_nop 0
	v_mul_f32_e32 v86, v86, v94
	v_mul_f32_e32 v86, v86, v82
	v_mul_f32_e32 v82, 0xbfb8aa3b, v95
	v_exp_f32_e32 v82, v82
	s_nop 0
	v_add_f32_e32 v82, 1.0, v82
	v_rcp_f32_e32 v82, v82
	s_nop 0
	v_mul_f32_e32 v82, v95, v82
	v_mul_f32_e32 v82, v82, v91
	v_mul_f32_e32 v91, 0xbfb8aa3b, v87
	v_exp_f32_e32 v91, v91
	v_cvt_pk_bf16_f32 v82, v90, v82
	s_nop 0
	v_add_f32_e32 v91, 1.0, v91
	v_rcp_f32_e32 v91, v91
	s_nop 0
	v_mul_f32_e32 v87, v87, v91
	v_mul_f32_e32 v91, 0xbfb8aa3b, v88
	v_exp_f32_e32 v91, v91
	v_mul_f32_e32 v87, v87, v83
	v_mul_f32_e32 v83, 0xbfb8aa3b, v96
	v_exp_f32_e32 v83, v83
	v_add_f32_e32 v91, 1.0, v91
	v_rcp_f32_e32 v91, v91
	v_add_f32_e32 v83, 1.0, v83
	v_rcp_f32_e32 v83, v83
	v_mul_f32_e32 v88, v88, v91
	v_mul_f32_e32 v88, v88, v84
	v_mul_f32_e32 v84, 0xbfb8aa3b, v97
	v_exp_f32_e32 v84, v84
	v_mul_f32_e32 v91, 0xbfb8aa3b, v89
	v_exp_f32_e32 v91, v91
	v_mul_f32_e32 v83, v96, v83
	v_add_f32_e32 v84, 1.0, v84
	v_rcp_f32_e32 v84, v84
	v_add_f32_e32 v91, 1.0, v91
	v_rcp_f32_e32 v91, v91
	v_mul_f32_e32 v83, v83, v92
	v_mul_f32_e32 v84, v97, v84
	v_mul_f32_e32 v84, v84, v93
	v_cvt_pk_bf16_f32 v83, v83, v84
	v_cvt_pk_bf16_f32 v84, v86, v87
	v_or_b32_e32 v86, 32, v144
	v_mul_f32_e32 v89, v89, v91
	v_mad_i64_i32 v[86:87], s[8:9], v86, s0, v[114:115]
	v_mul_f32_e32 v85, v89, v85
	v_lshl_add_u64 v[86:87], v[86:87], 0, v[116:117]
	v_cvt_pk_bf16_f32 v85, v88, v85
	global_store_dwordx4 v[86:87], v[82:85], off
	s_nop 1
	v_mul_f32_e32 v82, 0xbfb8aa3b, v78
	v_exp_f32_e32 v82, v82
	s_nop 0
	v_add_f32_e32 v82, 1.0, v82
	v_rcp_f32_e32 v82, v82
	s_nop 0
	v_mul_f32_e32 v78, v78, v82
	v_mul_f32_e32 v74, v78, v74
	v_mul_f32_e32 v78, 0xbfb8aa3b, v70
	v_exp_f32_e32 v78, v78
	s_nop 0
	v_add_f32_e32 v78, 1.0, v78
	v_rcp_f32_e32 v78, v78
	s_nop 0
	v_mul_f32_e32 v70, v70, v78
	v_mul_f32_e32 v70, v70, v66
	v_mul_f32_e32 v66, 0xbfb8aa3b, v79
	v_exp_f32_e32 v66, v66
	s_nop 0
	v_add_f32_e32 v66, 1.0, v66
	v_rcp_f32_e32 v66, v66
	s_nop 0
	v_mul_f32_e32 v66, v79, v66
	v_mul_f32_e32 v66, v66, v75
	v_mul_f32_e32 v75, 0xbfb8aa3b, v71
	v_exp_f32_e32 v75, v75
	v_cvt_pk_bf16_f32 v66, v74, v66
	s_nop 0
	v_add_f32_e32 v75, 1.0, v75
	v_rcp_f32_e32 v75, v75
	s_nop 0
	v_mul_f32_e32 v71, v71, v75
	v_mul_f32_e32 v75, 0xbfb8aa3b, v72
	v_exp_f32_e32 v75, v75
	v_mul_f32_e32 v71, v71, v67
	v_mul_f32_e32 v67, 0xbfb8aa3b, v80
	v_exp_f32_e32 v67, v67
	v_add_f32_e32 v75, 1.0, v75
	v_rcp_f32_e32 v75, v75
	v_add_f32_e32 v67, 1.0, v67
	v_rcp_f32_e32 v67, v67
	v_mul_f32_e32 v72, v72, v75
	v_mul_f32_e32 v72, v72, v68
	v_mul_f32_e32 v68, 0xbfb8aa3b, v81
	v_exp_f32_e32 v68, v68
	v_mul_f32_e32 v75, 0xbfb8aa3b, v73
	v_exp_f32_e32 v75, v75
	v_mul_f32_e32 v67, v80, v67
	v_add_f32_e32 v68, 1.0, v68
	v_rcp_f32_e32 v68, v68
	v_add_f32_e32 v75, 1.0, v75
	v_rcp_f32_e32 v75, v75
	v_mul_f32_e32 v67, v67, v76
	v_mul_f32_e32 v68, v81, v68
	v_mul_f32_e32 v68, v68, v77
	v_cvt_pk_bf16_f32 v67, v67, v68
	v_cvt_pk_bf16_f32 v68, v70, v71
	v_or_b32_e32 v70, 48, v144
	v_mul_f32_e32 v73, v73, v75
	v_mad_i64_i32 v[70:71], s[8:9], v70, s0, v[114:115]
	v_mul_f32_e32 v69, v73, v69
	v_lshl_add_u64 v[70:71], v[70:71], 0, v[116:117]
	v_cvt_pk_bf16_f32 v69, v72, v69
	global_store_dwordx4 v[70:71], v[66:69], off
	s_nop 1
	v_mul_f32_e32 v67, 0xbfb8aa3b, v62
	v_exp_f32_e32 v67, v67
	v_add_u32_e32 v66, 0x80, v144
	v_add_f32_e32 v67, 1.0, v67
	v_rcp_f32_e32 v67, v67
	s_nop 0
	v_mul_f32_e32 v62, v62, v67
	v_mul_f32_e32 v58, v62, v58
	v_mul_f32_e32 v62, 0xbfb8aa3b, v54
	v_exp_f32_e32 v62, v62
	s_nop 0
	v_add_f32_e32 v62, 1.0, v62
	v_rcp_f32_e32 v62, v62
	s_nop 0
	v_mul_f32_e32 v54, v54, v62
	v_mul_f32_e32 v54, v54, v50
	v_mul_f32_e32 v50, 0xbfb8aa3b, v63
	v_exp_f32_e32 v50, v50
	s_nop 0
	v_add_f32_e32 v50, 1.0, v50
	v_rcp_f32_e32 v50, v50
	s_nop 0
	v_mul_f32_e32 v50, v63, v50
	v_mul_f32_e32 v50, v50, v59
	v_mul_f32_e32 v59, 0xbfb8aa3b, v55
	v_exp_f32_e32 v59, v59
	v_cvt_pk_bf16_f32 v50, v58, v50
	s_nop 0
	v_add_f32_e32 v59, 1.0, v59
	v_rcp_f32_e32 v59, v59
	s_nop 0
	v_mul_f32_e32 v55, v55, v59
	v_mul_f32_e32 v59, 0xbfb8aa3b, v56
	v_exp_f32_e32 v59, v59
	v_mul_f32_e32 v55, v55, v51
	v_mul_f32_e32 v51, 0xbfb8aa3b, v64
	v_exp_f32_e32 v51, v51
	v_add_f32_e32 v59, 1.0, v59
	v_rcp_f32_e32 v59, v59
	v_add_f32_e32 v51, 1.0, v51
	v_rcp_f32_e32 v51, v51
	v_mul_f32_e32 v56, v56, v59
	v_mul_f32_e32 v56, v56, v52
	v_mul_f32_e32 v52, 0xbfb8aa3b, v65
	v_exp_f32_e32 v52, v52
	v_mul_f32_e32 v59, 0xbfb8aa3b, v57
	v_exp_f32_e32 v59, v59
	v_mul_f32_e32 v51, v64, v51
	v_add_f32_e32 v52, 1.0, v52
	v_rcp_f32_e32 v52, v52
	v_add_f32_e32 v59, 1.0, v59
	v_rcp_f32_e32 v59, v59
	v_mul_f32_e32 v51, v51, v60
	v_mul_f32_e32 v52, v65, v52
	v_mul_f32_e32 v52, v52, v61
	v_mul_f32_e32 v57, v57, v59
	v_cvt_pk_bf16_f32 v51, v51, v52
	v_cvt_pk_bf16_f32 v52, v54, v55
	v_mad_i64_i32 v[54:55], s[8:9], v66, s0, v[114:115]
	v_mul_f32_e32 v53, v57, v53
	v_lshl_add_u64 v[54:55], v[54:55], 0, v[116:117]
	v_cvt_pk_bf16_f32 v53, v56, v53
	global_store_dwordx4 v[54:55], v[50:53], off
	s_nop 1
	v_mul_f32_e32 v50, 0xbfb8aa3b, v46
	v_exp_f32_e32 v50, v50
	s_nop 0
	v_add_f32_e32 v50, 1.0, v50
	v_rcp_f32_e32 v50, v50
	s_nop 0
	v_mul_f32_e32 v46, v46, v50
	v_mul_f32_e32 v42, v46, v42
	v_mul_f32_e32 v46, 0xbfb8aa3b, v38
	v_exp_f32_e32 v46, v46
	s_nop 0
	v_add_f32_e32 v46, 1.0, v46
	v_rcp_f32_e32 v46, v46
	s_nop 0
	v_mul_f32_e32 v38, v38, v46
	v_mul_f32_e32 v38, v38, v34
	v_mul_f32_e32 v34, 0xbfb8aa3b, v47
	v_exp_f32_e32 v34, v34
	s_nop 0
	v_add_f32_e32 v34, 1.0, v34
	v_rcp_f32_e32 v34, v34
	s_nop 0
	v_mul_f32_e32 v34, v47, v34
	v_mul_f32_e32 v34, v34, v43
	v_mul_f32_e32 v43, 0xbfb8aa3b, v39
	v_exp_f32_e32 v43, v43
	v_cvt_pk_bf16_f32 v34, v42, v34
	s_nop 0
	v_add_f32_e32 v43, 1.0, v43
	v_rcp_f32_e32 v43, v43
	s_nop 0
	v_mul_f32_e32 v39, v39, v43
	v_mul_f32_e32 v43, 0xbfb8aa3b, v40
	v_exp_f32_e32 v43, v43
	v_mul_f32_e32 v39, v39, v35
	v_mul_f32_e32 v35, 0xbfb8aa3b, v48
	v_exp_f32_e32 v35, v35
	v_add_f32_e32 v43, 1.0, v43
	v_rcp_f32_e32 v43, v43
	v_add_f32_e32 v35, 1.0, v35
	v_rcp_f32_e32 v35, v35
	v_mul_f32_e32 v40, v40, v43
	v_mul_f32_e32 v40, v40, v36
	v_mul_f32_e32 v36, 0xbfb8aa3b, v49
	v_exp_f32_e32 v36, v36
	v_mul_f32_e32 v43, 0xbfb8aa3b, v41
	v_exp_f32_e32 v43, v43
	v_mul_f32_e32 v35, v48, v35
	v_add_f32_e32 v36, 1.0, v36
	v_rcp_f32_e32 v36, v36
	v_add_f32_e32 v43, 1.0, v43
	v_rcp_f32_e32 v43, v43
	v_mul_f32_e32 v35, v35, v44
	v_mul_f32_e32 v36, v49, v36
	v_mul_f32_e32 v36, v36, v45
	v_cvt_pk_bf16_f32 v35, v35, v36
	v_cvt_pk_bf16_f32 v36, v38, v39
	v_add_u32_e32 v38, 0x90, v144
	v_mul_f32_e32 v41, v41, v43
	v_mad_i64_i32 v[38:39], s[8:9], v38, s0, v[114:115]
	v_mul_f32_e32 v37, v41, v37
	v_lshl_add_u64 v[38:39], v[38:39], 0, v[116:117]
	v_cvt_pk_bf16_f32 v37, v40, v37
	global_store_dwordx4 v[38:39], v[34:37], off
	s_nop 1
	v_mul_f32_e32 v34, 0xbfb8aa3b, v30
	v_exp_f32_e32 v34, v34
	s_nop 0
	v_add_f32_e32 v34, 1.0, v34
	v_rcp_f32_e32 v34, v34
	s_nop 0
	v_mul_f32_e32 v30, v30, v34
	v_mul_f32_e32 v26, v30, v26
	v_mul_f32_e32 v30, 0xbfb8aa3b, v22
	v_exp_f32_e32 v30, v30
	s_nop 0
	v_add_f32_e32 v30, 1.0, v30
	v_rcp_f32_e32 v30, v30
	s_nop 0
	v_mul_f32_e32 v22, v22, v30
	v_mul_f32_e32 v22, v22, v18
	v_mul_f32_e32 v18, 0xbfb8aa3b, v31
	v_exp_f32_e32 v18, v18
	s_nop 0
	v_add_f32_e32 v18, 1.0, v18
	v_rcp_f32_e32 v18, v18
	s_nop 0
	v_mul_f32_e32 v18, v31, v18
	v_mul_f32_e32 v18, v18, v27
	v_mul_f32_e32 v27, 0xbfb8aa3b, v23
	v_exp_f32_e32 v27, v27
	v_cvt_pk_bf16_f32 v18, v26, v18
	s_nop 0
	v_add_f32_e32 v27, 1.0, v27
	v_rcp_f32_e32 v27, v27
	s_nop 0
	v_mul_f32_e32 v23, v23, v27
	v_mul_f32_e32 v27, 0xbfb8aa3b, v24
	v_exp_f32_e32 v27, v27
	v_mul_f32_e32 v23, v23, v19
	v_mul_f32_e32 v19, 0xbfb8aa3b, v32
	v_exp_f32_e32 v19, v19
	v_add_f32_e32 v27, 1.0, v27
	v_rcp_f32_e32 v27, v27
	v_add_f32_e32 v19, 1.0, v19
	v_rcp_f32_e32 v19, v19
	v_mul_f32_e32 v24, v24, v27
	v_mul_f32_e32 v24, v24, v20
	v_mul_f32_e32 v20, 0xbfb8aa3b, v33
	v_exp_f32_e32 v20, v20
	v_mul_f32_e32 v27, 0xbfb8aa3b, v25
	v_exp_f32_e32 v27, v27
	v_mul_f32_e32 v19, v32, v19
	v_add_f32_e32 v20, 1.0, v20
	v_rcp_f32_e32 v20, v20
	v_add_f32_e32 v27, 1.0, v27
	v_rcp_f32_e32 v27, v27
	v_mul_f32_e32 v19, v19, v28
	v_mul_f32_e32 v20, v33, v20
	v_mul_f32_e32 v20, v20, v29
	v_cvt_pk_bf16_f32 v19, v19, v20
	v_cvt_pk_bf16_f32 v20, v22, v23
	v_add_u32_e32 v22, 0xa0, v144
	v_mul_f32_e32 v25, v25, v27
	v_mad_i64_i32 v[22:23], s[8:9], v22, s0, v[114:115]
	v_mul_f32_e32 v21, v25, v21
	v_lshl_add_u64 v[22:23], v[22:23], 0, v[116:117]
	v_cvt_pk_bf16_f32 v21, v24, v21
	global_store_dwordx4 v[22:23], v[18:21], off
	s_nop 1
	v_mul_f32_e32 v18, 0xbfb8aa3b, v14
	v_exp_f32_e32 v18, v18
	s_nop 0
	v_add_f32_e32 v18, 1.0, v18
	v_rcp_f32_e32 v18, v18
	s_nop 0
	v_mul_f32_e32 v14, v14, v18
	v_mul_f32_e32 v10, v14, v10
	v_mul_f32_e32 v14, 0xbfb8aa3b, v6
	v_exp_f32_e32 v14, v14
	s_nop 0
	v_add_f32_e32 v14, 1.0, v14
	v_rcp_f32_e32 v14, v14
	s_nop 0
	v_mul_f32_e32 v6, v6, v14
	v_mul_f32_e32 v6, v6, v2
	v_mul_f32_e32 v2, 0xbfb8aa3b, v15
	v_exp_f32_e32 v2, v2
	s_nop 0
	v_add_f32_e32 v2, 1.0, v2
	v_rcp_f32_e32 v2, v2
	s_nop 0
	v_mul_f32_e32 v2, v15, v2
	v_mul_f32_e32 v2, v2, v11
	v_mul_f32_e32 v11, 0xbfb8aa3b, v7
	v_exp_f32_e32 v11, v11
	v_cvt_pk_bf16_f32 v2, v10, v2
	s_nop 0
	v_add_f32_e32 v11, 1.0, v11
	v_rcp_f32_e32 v11, v11
	s_nop 0
	v_mul_f32_e32 v7, v7, v11
	v_mul_f32_e32 v11, 0xbfb8aa3b, v8
	v_exp_f32_e32 v11, v11
	v_mul_f32_e32 v7, v7, v3
	v_mul_f32_e32 v3, 0xbfb8aa3b, v16
	v_exp_f32_e32 v3, v3
	v_add_f32_e32 v11, 1.0, v11
	v_rcp_f32_e32 v11, v11
	v_add_f32_e32 v3, 1.0, v3
	v_rcp_f32_e32 v3, v3
	v_mul_f32_e32 v8, v8, v11
	v_mul_f32_e32 v8, v8, v4
	v_mul_f32_e32 v4, 0xbfb8aa3b, v17
	v_exp_f32_e32 v4, v4
	v_mul_f32_e32 v11, 0xbfb8aa3b, v9
	v_exp_f32_e32 v11, v11
	v_mul_f32_e32 v3, v16, v3
	v_add_f32_e32 v4, 1.0, v4
	v_rcp_f32_e32 v4, v4
	v_add_f32_e32 v11, 1.0, v11
	v_rcp_f32_e32 v11, v11
	v_mul_f32_e32 v3, v3, v12
	v_mul_f32_e32 v4, v17, v4
	v_mul_f32_e32 v4, v4, v13
	v_cvt_pk_bf16_f32 v3, v3, v4
	v_cvt_pk_bf16_f32 v4, v6, v7
	v_add_u32_e32 v6, 0xb0, v144
	v_mul_f32_e32 v9, v9, v11
	v_mad_i64_i32 v[6:7], s[8:9], v6, s0, v[114:115]
	v_mul_f32_e32 v5, v9, v5
	v_lshl_add_u64 v[6:7], v[6:7], 0, v[116:117]
	s_mov_b64 s[8:9], -1
	v_cvt_pk_bf16_f32 v5, v8, v5
	global_store_dwordx4 v[6:7], v[2:5], off
	s_setprio 0
	s_cbranch_vccnz .LBB0_894
	s_andn2_b64 vcc, exec, s[4:5]
	s_cbranch_vccnz .LBB0_893
	s_mov_b32 s100, 1
	s_branch .LBB0_893

.Lkmid_4:
	s_add_i32 s78, 0, 0x18000
	s_add_i32 s79, 0, 0x1c000
	ds_read_b128 v[130:133], v250 offset:32768
	ds_read_b128 v[134:137], v250 offset:33792
	ds_read_b128 v[138:141], v250 offset:34816
	ds_read_b128 v[142:145], v250 offset:35840
	ds_read_b128 v[146:149], v250 offset:49152
	ds_read_b128 v[150:153], v250 offset:50176
	ds_read_b128 v[154:157], v250 offset:51200
	ds_read_b128 v[158:161], v250 offset:52224
	s_add_u32 s0, s64, 0x80000
	s_addc_u32 s1, s65, 0
	s_mov_b32 m0, s29
	ds_read_b128 v[162:165], v189 offset:32768
	ds_read_b128 v[180:183], v189 offset:33792
	ds_read_b128 v[184:187], v189 offset:34816
	ds_read_b128 v[190:193], v189 offset:35840
	ds_read_b128 v[202:205], v189 offset:36864
	ds_read_b128 v[206:209], v189 offset:37888
	ds_read_b128 v[210:213], v189 offset:38912
	ds_read_b128 v[214:217], v189 offset:39936
	global_load_lds_dwordx4 v166, s[0:1]
	s_mov_b32 m0, s30
	s_nop 0
	global_load_lds_dwordx4 v168, s[0:1]
	s_waitcnt vmcnt(8)
	s_waitcnt lgkmcnt(0)
	s_setprio 1
	s_barrier
	v_mfma_f32_16x16x32_bf16 v[126:129], v[130:133], v[162:165], v[126:129]
	v_mfma_f32_16x16x32_bf16 v[122:125], v[138:141], v[162:165], v[122:125]
	v_mfma_f32_16x16x32_bf16 v[110:113], v[130:133], v[184:187], v[110:113]
	v_mfma_f32_16x16x32_bf16 v[106:109], v[138:141], v[184:187], v[106:109]
	v_mfma_f32_16x16x32_bf16 v[98:101], v[130:133], v[202:205], v[98:101]
	v_mfma_f32_16x16x32_bf16 v[90:93], v[138:141], v[202:205], v[90:93]
	v_mfma_f32_16x16x32_bf16 v[82:85], v[130:133], v[210:213], v[82:85]
	v_mfma_f32_16x16x32_bf16 v[74:77], v[138:141], v[210:213], v[74:77]
	v_mfma_f32_16x16x32_bf16 v[126:129], v[134:137], v[180:183], v[126:129]
	v_mfma_f32_16x16x32_bf16 v[122:125], v[142:145], v[180:183], v[122:125]
	v_mfma_f32_16x16x32_bf16 v[110:113], v[134:137], v[190:193], v[110:113]
	v_mfma_f32_16x16x32_bf16 v[106:109], v[142:145], v[190:193], v[106:109]
	v_mfma_f32_16x16x32_bf16 v[98:101], v[134:137], v[206:209], v[98:101]
	v_mfma_f32_16x16x32_bf16 v[90:93], v[142:145], v[206:209], v[90:93]
	v_mfma_f32_16x16x32_bf16 v[82:85], v[134:137], v[214:217], v[82:85]
	v_mfma_f32_16x16x32_bf16 v[74:77], v[142:145], v[214:217], v[74:77]
	v_mfma_f32_16x16x32_bf16 v[118:121], v[146:149], v[162:165], v[118:121]
	v_mfma_f32_16x16x32_bf16 v[114:117], v[154:157], v[162:165], v[114:117]
	v_mfma_f32_16x16x32_bf16 v[102:105], v[146:149], v[184:187], v[102:105]
	v_mfma_f32_16x16x32_bf16 v[94:97], v[154:157], v[184:187], v[94:97]
	v_mfma_f32_16x16x32_bf16 v[86:89], v[146:149], v[202:205], v[86:89]
	v_mfma_f32_16x16x32_bf16 v[78:81], v[154:157], v[202:205], v[78:81]
	v_mfma_f32_16x16x32_bf16 v[70:73], v[146:149], v[210:213], v[70:73]
	v_mfma_f32_16x16x32_bf16 v[66:69], v[154:157], v[210:213], v[66:69]
	v_mfma_f32_16x16x32_bf16 v[118:121], v[150:153], v[180:183], v[118:121]
	v_mfma_f32_16x16x32_bf16 v[114:117], v[158:161], v[180:183], v[114:117]
	v_mfma_f32_16x16x32_bf16 v[102:105], v[150:153], v[190:193], v[102:105]
	v_mfma_f32_16x16x32_bf16 v[94:97], v[158:161], v[190:193], v[94:97]
	v_mfma_f32_16x16x32_bf16 v[86:89], v[150:153], v[206:209], v[86:89]
	v_mfma_f32_16x16x32_bf16 v[78:81], v[158:161], v[206:209], v[78:81]
	v_mfma_f32_16x16x32_bf16 v[70:73], v[150:153], v[214:217], v[70:73]
	v_mfma_f32_16x16x32_bf16 v[66:69], v[158:161], v[214:217], v[66:69]
	s_barrier
	s_setprio 0
	s_add_i32 s0, s78, s26
	s_mov_b32 m0, s0
	ds_read_b128 v[162:165], v189 offset:49152
	ds_read_b128 v[180:183], v189 offset:50176
	ds_read_b128 v[184:187], v189 offset:51200
	ds_read_b128 v[190:193], v189 offset:52224
	ds_read_b128 v[202:205], v189 offset:53248
	ds_read_b128 v[206:209], v189 offset:54272
	ds_read_b128 v[210:213], v189 offset:55296
	ds_read_b128 v[214:217], v189 offset:56320
	global_load_lds_dwordx4 v196, s[98:99]
	s_add_i32 m0, s0, 0x2000
	s_add_u32 s0, s8, 0x80080
	s_addc_u32 s1, s9, 0
	s_add_i32 s8, s79, s26
	global_load_lds_dwordx4 v170, s[98:99]
	s_mov_b32 m0, s8
	s_nop 0
	global_load_lds_dwordx4 v196, s[0:1]
	s_add_i32 m0, s8, 0x2000
	s_nop 0
	global_load_lds_dwordx4 v170, s[0:1]
	v_lshl_add_u64 v[194:195], v[220:221], 0, s[16:17]
	s_mov_b32 m0, s35
	s_nop 0
	global_load_lds_dwordx4 v[194:195], off
	v_lshl_add_u64 v[194:195], v[222:223], 0, s[16:17]
	s_mov_b32 m0, s53
	s_nop 0
	global_load_lds_dwordx4 v[194:195], off
	s_waitcnt vmcnt(8)
	s_waitcnt lgkmcnt(0)
	s_setprio 1
	s_barrier
	v_mfma_f32_16x16x32_bf16 v[62:65], v[130:133], v[162:165], v[62:65]
	v_mfma_f32_16x16x32_bf16 v[58:61], v[138:141], v[162:165], v[58:61]
	v_mfma_f32_16x16x32_bf16 v[50:53], v[130:133], v[184:187], v[50:53]
	v_mfma_f32_16x16x32_bf16 v[42:45], v[138:141], v[184:187], v[42:45]
	v_mfma_f32_16x16x32_bf16 v[34:37], v[130:133], v[202:205], v[34:37]
	v_mfma_f32_16x16x32_bf16 v[26:29], v[138:141], v[202:205], v[26:29]
	v_mfma_f32_16x16x32_bf16 v[18:21], v[130:133], v[210:213], v[18:21]
	v_mfma_f32_16x16x32_bf16 v[10:13], v[138:141], v[210:213], v[10:13]
	v_mfma_f32_16x16x32_bf16 v[62:65], v[134:137], v[180:183], v[62:65]
	v_mfma_f32_16x16x32_bf16 v[58:61], v[142:145], v[180:183], v[58:61]
	v_mfma_f32_16x16x32_bf16 v[50:53], v[134:137], v[190:193], v[50:53]
	v_mfma_f32_16x16x32_bf16 v[42:45], v[142:145], v[190:193], v[42:45]
	v_mfma_f32_16x16x32_bf16 v[34:37], v[134:137], v[206:209], v[34:37]
	v_mfma_f32_16x16x32_bf16 v[26:29], v[142:145], v[206:209], v[26:29]
	v_mfma_f32_16x16x32_bf16 v[18:21], v[134:137], v[214:217], v[18:21]
	v_mfma_f32_16x16x32_bf16 v[10:13], v[142:145], v[214:217], v[10:13]
	v_mfma_f32_16x16x32_bf16 v[54:57], v[146:149], v[162:165], v[54:57]
	v_mfma_f32_16x16x32_bf16 v[46:49], v[154:157], v[162:165], v[46:49]
	v_mfma_f32_16x16x32_bf16 v[38:41], v[146:149], v[184:187], v[38:41]
	v_mfma_f32_16x16x32_bf16 v[30:33], v[154:157], v[184:187], v[30:33]
	v_mfma_f32_16x16x32_bf16 v[22:25], v[146:149], v[202:205], v[22:25]
	v_mfma_f32_16x16x32_bf16 v[14:17], v[154:157], v[202:205], v[14:17]
	v_mfma_f32_16x16x32_bf16 v[6:9], v[146:149], v[210:213], v[6:9]
	v_mfma_f32_16x16x32_bf16 v[2:5], v[154:157], v[210:213], v[2:5]
	v_mfma_f32_16x16x32_bf16 v[54:57], v[150:153], v[180:183], v[54:57]
	v_mfma_f32_16x16x32_bf16 v[46:49], v[158:161], v[180:183], v[46:49]
	v_mfma_f32_16x16x32_bf16 v[38:41], v[150:153], v[190:193], v[38:41]
	v_mfma_f32_16x16x32_bf16 v[30:33], v[158:161], v[190:193], v[30:33]
	v_mfma_f32_16x16x32_bf16 v[22:25], v[150:153], v[206:209], v[22:25]
	v_mfma_f32_16x16x32_bf16 v[14:17], v[158:161], v[206:209], v[14:17]
	v_mfma_f32_16x16x32_bf16 v[6:9], v[150:153], v[214:217], v[6:9]
	v_mfma_f32_16x16x32_bf16 v[2:5], v[158:161], v[214:217], v[2:5]
	s_barrier
	s_setprio 0
	s_add_u32 s72, s72, 0x100
	s_addc_u32 s73, s73, 0
	s_add_u32 s62, s62, 0x100
	s_addc_u32 s63, s63, 0
	s_cmp_ge_i32 s77, s69
	s_mov_b32 s8, s77
	s_cbranch_scc0 .LBB0_2357
	s_and_b64 vcc, exec, s[38:39]
	s_cbranch_vccz .LBB0_2360
	s_barrier
	s_setprio 1

.LBB0_2363:
	s_setprio 0
	s_andn2_b64 vcc, exec, s[46:47]
	s_mov_b64 s[8:9], -1
	s_cbranch_vccnz .LBB0_2346
	s_andn2_b64 vcc, exec, s[4:5]
	s_cbranch_vccnz .LBB0_2345
	s_mov_b32 s100, 1
	s_branch .LBB0_2345
